# v35 + PV block's first four V^T LDS reads hoisted above the softmax row-max tree (max temporaries renamed to free registers)
# baseline (speedup 1.0000x reference)
; template <int DQK, bool CAUSAL, bool ROPE> ...
;     ...
;         if (grp == 1 && j > 0) AT_PV(j - 1, vprev);
.LBB0_885:
	s_cmp_eq_u32 s92, 0
	s_cselect_b64 s[4:5], -1, 0
	s_or_b64 s[4:5], s[86:87], s[4:5]
	s_sub_i32 s6, s92, 64
	s_cmp_gt_i32 s6, s64
	s_cselect_b64 s[6:7], -1, 0
	s_or_b64 s[4:5], s[4:5], s[6:7]
	s_and_b64 vcc, exec, s[4:5]
	s_cbranch_vccnz .LBB0_893
	s_mulk_i32 s0, 0x4800
	v_add_u32_e32 v17, s0, v244
	ds_read_b128 v[4:7], v17 offset:51200
	ds_read_b128 v[8:11], v17 offset:55808
	ds_read_b128 v[12:15], v17 offset:60416
	ds_read_b128 v[176:179], v17 offset:65024
	s_nop 8
	v_max3_f32 v2, v98, v99, v100
	v_max3_f32 v16, v101, v102, v103
	v_max3_f32 v174, v104, v105, v106
	v_max3_f32 v175, v107, v108, v109
	v_max3_f32 v2, v2, v110, v111
	v_max3_f32 v16, v16, v112, v113
	v_max3_f32 v174, v174, v82, v83
	v_max3_f32 v175, v175, v84, v85
	v_max3_f32 v2, v2, v86, v87
	v_max3_f32 v16, v16, v88, v89
	v_max3_f32 v174, v174, v90, v91
	v_max3_f32 v175, v175, v92, v93
	v_max3_f32 v2, v2, v94, v95
	v_max3_f32 v16, v16, v96, v97
	v_max3_f32 v2, v2, v16, v174
	v_max_f32_e32 v2, v2, v175
	v_mov_b32_e32 v16, v2
	s_nop 1
	v_permlane32_swap_b32_e32 v2, v16
	v_max_f32_e32 v2, v2, v16
	v_sub_f32_e32 v16, v2, v252
	v_mul_f32_e32 v16, 0x3dd53b94, v16
	s_mov_b32 s0, 0x41380000
	v_cmp_ge_f32_e32 vcc, s0, v16
	s_cmp_eq_u64 vcc, exec
	s_cbranch_scc1 .Ld2_exp
	v_max_f32_e32 v2, v2, v2
	v_max_f32_e32 v16, v252, v252
	v_max_f32_e32 v16, v16, v2
	v_sub_f32_e32 v2, v252, v16
	v_mul_f32_e32 v2, 0x3dd53b94, v2
	v_exp_f32_e32 v2, v2
	v_mov_b32_e32 v252, v16
	v_pk_mul_f32 v[80:81], v[80:81], v[2:3] op_sel_hi:[1,0]
	v_pk_mul_f32 v[78:79], v[78:79], v[2:3] op_sel_hi:[1,0]
	v_pk_mul_f32 v[76:77], v[76:77], v[2:3] op_sel_hi:[1,0]
	v_pk_mul_f32 v[74:75], v[74:75], v[2:3] op_sel_hi:[1,0]
	v_pk_mul_f32 v[72:73], v[72:73], v[2:3] op_sel_hi:[1,0]
	v_pk_mul_f32 v[70:71], v[70:71], v[2:3] op_sel_hi:[1,0]
	v_pk_mul_f32 v[68:69], v[68:69], v[2:3] op_sel_hi:[1,0]
	v_pk_mul_f32 v[66:67], v[66:67], v[2:3] op_sel_hi:[1,0]
	v_pk_mul_f32 v[64:65], v[64:65], v[2:3] op_sel_hi:[1,0]
	v_pk_mul_f32 v[62:63], v[62:63], v[2:3] op_sel_hi:[1,0]
	v_pk_mul_f32 v[60:61], v[60:61], v[2:3] op_sel_hi:[1,0]
	v_pk_mul_f32 v[58:59], v[58:59], v[2:3] op_sel_hi:[1,0]
	v_pk_mul_f32 v[56:57], v[56:57], v[2:3] op_sel_hi:[1,0]
	v_pk_mul_f32 v[54:55], v[54:55], v[2:3] op_sel_hi:[1,0]
	v_pk_mul_f32 v[52:53], v[52:53], v[2:3] op_sel_hi:[1,0]
	v_pk_mul_f32 v[50:51], v[50:51], v[2:3] op_sel_hi:[1,0]
	v_pk_mul_f32 v[48:49], v[48:49], v[2:3] op_sel_hi:[1,0]
	v_pk_mul_f32 v[46:47], v[46:47], v[2:3] op_sel_hi:[1,0]
	v_pk_mul_f32 v[44:45], v[44:45], v[2:3] op_sel_hi:[1,0]
	v_pk_mul_f32 v[42:43], v[42:43], v[2:3] op_sel_hi:[1,0]
	v_pk_mul_f32 v[40:41], v[40:41], v[2:3] op_sel_hi:[1,0]
	v_pk_mul_f32 v[38:39], v[38:39], v[2:3] op_sel_hi:[1,0]
	v_pk_mul_f32 v[36:37], v[36:37], v[2:3] op_sel_hi:[1,0]
	v_pk_mul_f32 v[34:35], v[34:35], v[2:3] op_sel_hi:[1,0]
	v_pk_mul_f32 v[32:33], v[32:33], v[2:3] op_sel_hi:[1,0]
	v_pk_mul_f32 v[30:31], v[30:31], v[2:3] op_sel_hi:[1,0]
	v_pk_mul_f32 v[28:29], v[28:29], v[2:3] op_sel_hi:[1,0]
	v_pk_mul_f32 v[26:27], v[26:27], v[2:3] op_sel_hi:[1,0]
	v_pk_mul_f32 v[24:25], v[24:25], v[2:3] op_sel_hi:[1,0]
	v_pk_mul_f32 v[22:23], v[22:23], v[2:3] op_sel_hi:[1,0]
	v_pk_mul_f32 v[20:21], v[20:21], v[2:3] op_sel_hi:[1,0]
	v_pk_mul_f32 v[18:19], v[18:19], v[2:3] op_sel_hi:[1,0]
	v_mul_f32_e32 v250, v250, v2
.Ld2_exp:
	v_mul_f32_e32 v2, 0xbdd53b94, v252
	v_fmamk_f32 v98, v98, 0x3dd53b94, v2
	v_fmamk_f32 v99, v99, 0x3dd53b94, v2
	v_fmamk_f32 v100, v100, 0x3dd53b94, v2
	v_fmamk_f32 v101, v101, 0x3dd53b94, v2
	v_fmamk_f32 v102, v102, 0x3dd53b94, v2
	v_fmamk_f32 v103, v103, 0x3dd53b94, v2
	v_fmamk_f32 v104, v104, 0x3dd53b94, v2
	v_fmamk_f32 v105, v105, 0x3dd53b94, v2
	v_exp_f32_e32 v98, v98
	v_exp_f32_e32 v99, v99
	v_exp_f32_e32 v100, v100
	v_exp_f32_e32 v101, v101
	v_exp_f32_e32 v102, v102
	v_exp_f32_e32 v103, v103
	v_exp_f32_e32 v104, v104
	v_exp_f32_e32 v105, v105
	v_add_f32_e32 v16, v98, v99
	v_add_f32_e32 v16, v16, v100
	v_add_f32_e32 v16, v16, v101
	v_add_f32_e32 v16, v16, v102
	v_add_f32_e32 v16, v16, v103
	v_add_f32_e32 v16, v16, v104
	v_add_f32_e32 v16, v16, v105
	v_cvt_pk_bf16_f32 v98, v98, v99
	v_cvt_pk_bf16_f32 v99, v100, v101
	v_cvt_pk_bf16_f32 v100, v102, v103
	v_cvt_pk_bf16_f32 v101, v104, v105
	v_fmamk_f32 v106, v106, 0x3dd53b94, v2
	s_waitcnt lgkmcnt(3)
	v_mfma_f32_32x32x16_bf16 v[66:81], v[4:7], v[98:101], v[66:81]
	ds_read_b128 v[4:7], v17 offset:51232
	v_fmamk_f32 v107, v107, 0x3dd53b94, v2
	v_fmamk_f32 v108, v108, 0x3dd53b94, v2
	v_fmamk_f32 v109, v109, 0x3dd53b94, v2
	v_fmamk_f32 v110, v110, 0x3dd53b94, v2
	v_fmamk_f32 v111, v111, 0x3dd53b94, v2
	v_fmamk_f32 v112, v112, 0x3dd53b94, v2
	s_waitcnt lgkmcnt(3)
	v_mfma_f32_32x32x16_bf16 v[50:65], v[8:11], v[98:101], v[50:65]
	ds_read_b128 v[8:11], v17 offset:55840
	v_fmamk_f32 v113, v113, 0x3dd53b94, v2
	v_exp_f32_e32 v106, v106
	v_exp_f32_e32 v107, v107
	v_exp_f32_e32 v108, v108
	v_exp_f32_e32 v109, v109
	v_exp_f32_e32 v110, v110
	s_waitcnt lgkmcnt(3)
	v_mfma_f32_32x32x16_bf16 v[34:49], v[12:15], v[98:101], v[34:49]
	ds_read_b128 v[12:15], v17 offset:60448
	v_exp_f32_e32 v111, v111
	v_exp_f32_e32 v112, v112
	v_exp_f32_e32 v113, v113
	v_pk_add_f32 v[102:103], v[106:107], v[108:109]
	v_pk_add_f32 v[104:105], v[110:111], v[112:113]
	s_waitcnt lgkmcnt(3)
	v_mfma_f32_32x32x16_bf16 v[18:33], v[176:179], v[98:101], v[18:33]
	ds_read_b128 v[176:179], v17 offset:65056
	v_pk_add_f32 v[102:103], v[102:103], v[104:105]
	v_cvt_pk_bf16_f32 v106, v106, v107
	v_cvt_pk_bf16_f32 v107, v108, v109
	v_cvt_pk_bf16_f32 v108, v110, v111
	v_cvt_pk_bf16_f32 v109, v112, v113
	v_fmamk_f32 v82, v82, 0x3dd53b94, v2
	s_waitcnt lgkmcnt(3)
	v_mfma_f32_32x32x16_bf16 v[66:81], v[4:7], v[106:109], v[66:81]
	ds_read_b128 v[4:7], v17 offset:51264
	v_fmamk_f32 v83, v83, 0x3dd53b94, v2
	v_fmamk_f32 v84, v84, 0x3dd53b94, v2
	v_fmamk_f32 v85, v85, 0x3dd53b94, v2
	v_fmamk_f32 v86, v86, 0x3dd53b94, v2
	v_fmamk_f32 v87, v87, 0x3dd53b94, v2
	v_fmamk_f32 v88, v88, 0x3dd53b94, v2
	s_waitcnt lgkmcnt(3)
	v_mfma_f32_32x32x16_bf16 v[50:65], v[8:11], v[106:109], v[50:65]
	ds_read_b128 v[8:11], v17 offset:55872
	v_fmamk_f32 v89, v89, 0x3dd53b94, v2
	v_exp_f32_e32 v82, v82
	v_exp_f32_e32 v83, v83
	v_exp_f32_e32 v84, v84
	v_exp_f32_e32 v85, v85
	v_exp_f32_e32 v86, v86
	s_waitcnt lgkmcnt(3)
	v_mfma_f32_32x32x16_bf16 v[34:49], v[12:15], v[106:109], v[34:49]
	ds_read_b128 v[12:15], v17 offset:60480
	v_exp_f32_e32 v87, v87
	v_exp_f32_e32 v88, v88
	v_exp_f32_e32 v89, v89
	v_pk_add_f32 v[104:105], v[82:83], v[84:85]
	v_pk_add_f32 v[102:103], v[102:103], v[104:105]
	v_pk_add_f32 v[104:105], v[86:87], v[88:89]
	s_waitcnt lgkmcnt(3)
	v_mfma_f32_32x32x16_bf16 v[18:33], v[176:179], v[106:109], v[18:33]
	ds_read_b128 v[176:179], v17 offset:65088
	v_pk_add_f32 v[102:103], v[102:103], v[104:105]
	v_cvt_pk_bf16_f32 v82, v82, v83
	v_cvt_pk_bf16_f32 v83, v84, v85
	v_cvt_pk_bf16_f32 v84, v86, v87
	v_cvt_pk_bf16_f32 v85, v88, v89
	v_fmamk_f32 v90, v90, 0x3dd53b94, v2
	s_waitcnt lgkmcnt(3)
	v_mfma_f32_32x32x16_bf16 v[66:81], v[4:7], v[82:85], v[66:81]
	ds_read_b128 v[4:7], v17 offset:51296
	v_fmamk_f32 v91, v91, 0x3dd53b94, v2
	v_fmamk_f32 v92, v92, 0x3dd53b94, v2
	v_fmamk_f32 v93, v93, 0x3dd53b94, v2
	v_fmamk_f32 v94, v94, 0x3dd53b94, v2
	v_fmamk_f32 v95, v95, 0x3dd53b94, v2
	v_fmamk_f32 v96, v96, 0x3dd53b94, v2
	s_waitcnt lgkmcnt(3)
	v_mfma_f32_32x32x16_bf16 v[50:65], v[8:11], v[82:85], v[50:65]
	ds_read_b128 v[8:11], v17 offset:55904
	v_fmamk_f32 v97, v97, 0x3dd53b94, v2
	v_exp_f32_e32 v90, v90
	v_exp_f32_e32 v91, v91
	v_exp_f32_e32 v92, v92
	v_exp_f32_e32 v93, v93
	v_exp_f32_e32 v94, v94
	s_waitcnt lgkmcnt(3)
	v_mfma_f32_32x32x16_bf16 v[34:49], v[12:15], v[82:85], v[34:49]
	ds_read_b128 v[12:15], v17 offset:60512
	v_exp_f32_e32 v95, v95
	v_exp_f32_e32 v96, v96
	v_exp_f32_e32 v97, v97
	v_pk_add_f32 v[104:105], v[90:91], v[92:93]
	v_pk_add_f32 v[102:103], v[102:103], v[104:105]
	v_pk_add_f32 v[104:105], v[94:95], v[96:97]
	s_waitcnt lgkmcnt(3)
	v_mfma_f32_32x32x16_bf16 v[18:33], v[176:179], v[82:85], v[18:33]
	ds_read_b128 v[176:179], v17 offset:65120
	v_pk_add_f32 v[102:103], v[102:103], v[104:105]
	v_cvt_pk_bf16_f32 v90, v90, v91
	v_cvt_pk_bf16_f32 v91, v92, v93
	v_cvt_pk_bf16_f32 v92, v94, v95
	v_cvt_pk_bf16_f32 v93, v96, v97
	s_nop 0
	s_waitcnt lgkmcnt(3)
	v_mfma_f32_32x32x16_bf16 v[66:81], v[4:7], v[90:93], v[66:81]
	v_add_f32_e32 v16, v16, v102
	s_waitcnt lgkmcnt(2)
	v_mfma_f32_32x32x16_bf16 v[50:65], v[8:11], v[90:93], v[50:65]
	v_add_f32_e32 v16, v16, v103
	s_waitcnt lgkmcnt(1)
	v_mfma_f32_32x32x16_bf16 v[34:49], v[12:15], v[90:93], v[34:49]
	v_add_f32_e32 v250, v250, v16
	s_waitcnt lgkmcnt(0)
	v_mfma_f32_32x32x16_bf16 v[18:33], v[176:179], v[90:93], v[18:33]
	s_branch .LBB0_893

.LBB0_896:
	s_and_b64 vcc, exec, s[84:85]
	s_cbranch_vccnz .LBB0_889
	s_mul_i32 s0, s71, 0x4800
	v_add_u32_e32 v17, s0, v244
	ds_read_b128 v[4:7], v17 offset:51200
	ds_read_b128 v[8:11], v17 offset:55808
	ds_read_b128 v[12:15], v17 offset:60416
	ds_read_b128 v[176:179], v17 offset:65024
	s_nop 8
	v_max3_f32 v2, v98, v99, v100
	v_max3_f32 v16, v101, v102, v103
	v_max3_f32 v174, v104, v105, v106
	v_max3_f32 v175, v107, v108, v109
	v_max3_f32 v2, v2, v110, v111
	v_max3_f32 v16, v16, v112, v113
	v_max3_f32 v174, v174, v82, v83
	v_max3_f32 v175, v175, v84, v85
	v_max3_f32 v2, v2, v86, v87
	v_max3_f32 v16, v16, v88, v89
	v_max3_f32 v174, v174, v90, v91
	v_max3_f32 v175, v175, v92, v93
	v_max3_f32 v2, v2, v94, v95
	v_max3_f32 v16, v16, v96, v97
	v_max3_f32 v2, v2, v16, v174
	v_max_f32_e32 v2, v2, v175
	v_mov_b32_e32 v16, v2
	s_nop 1
	v_permlane32_swap_b32_e32 v2, v16
	v_max_f32_e32 v2, v2, v16
	v_sub_f32_e32 v16, v2, v252
	v_mul_f32_e32 v16, 0x3dd53b94, v16
	s_mov_b32 s0, 0x41380000
	v_cmp_ge_f32_e32 vcc, s0, v16
	s_cmp_eq_u64 vcc, exec
	s_cbranch_scc1 .Ld1_exp
	v_max_f32_e32 v2, v2, v2
	v_max_f32_e32 v16, v252, v252
	v_max_f32_e32 v16, v16, v2
	v_sub_f32_e32 v2, v252, v16
	v_mul_f32_e32 v2, 0x3dd53b94, v2
	v_exp_f32_e32 v2, v2
	v_mov_b32_e32 v252, v16
	v_pk_mul_f32 v[80:81], v[80:81], v[2:3] op_sel_hi:[1,0]
	v_pk_mul_f32 v[78:79], v[78:79], v[2:3] op_sel_hi:[1,0]
	v_pk_mul_f32 v[76:77], v[76:77], v[2:3] op_sel_hi:[1,0]
	v_pk_mul_f32 v[74:75], v[74:75], v[2:3] op_sel_hi:[1,0]
	v_pk_mul_f32 v[72:73], v[72:73], v[2:3] op_sel_hi:[1,0]
	v_pk_mul_f32 v[70:71], v[70:71], v[2:3] op_sel_hi:[1,0]
	v_pk_mul_f32 v[68:69], v[68:69], v[2:3] op_sel_hi:[1,0]
	v_pk_mul_f32 v[66:67], v[66:67], v[2:3] op_sel_hi:[1,0]
	v_pk_mul_f32 v[64:65], v[64:65], v[2:3] op_sel_hi:[1,0]
	v_pk_mul_f32 v[62:63], v[62:63], v[2:3] op_sel_hi:[1,0]
	v_pk_mul_f32 v[60:61], v[60:61], v[2:3] op_sel_hi:[1,0]
	v_pk_mul_f32 v[58:59], v[58:59], v[2:3] op_sel_hi:[1,0]
	v_pk_mul_f32 v[56:57], v[56:57], v[2:3] op_sel_hi:[1,0]
	v_pk_mul_f32 v[54:55], v[54:55], v[2:3] op_sel_hi:[1,0]
	v_pk_mul_f32 v[52:53], v[52:53], v[2:3] op_sel_hi:[1,0]
	v_pk_mul_f32 v[50:51], v[50:51], v[2:3] op_sel_hi:[1,0]
	v_pk_mul_f32 v[48:49], v[48:49], v[2:3] op_sel_hi:[1,0]
	v_pk_mul_f32 v[46:47], v[46:47], v[2:3] op_sel_hi:[1,0]
	v_pk_mul_f32 v[44:45], v[44:45], v[2:3] op_sel_hi:[1,0]
	v_pk_mul_f32 v[42:43], v[42:43], v[2:3] op_sel_hi:[1,0]
	v_pk_mul_f32 v[40:41], v[40:41], v[2:3] op_sel_hi:[1,0]
	v_pk_mul_f32 v[38:39], v[38:39], v[2:3] op_sel_hi:[1,0]
	v_pk_mul_f32 v[36:37], v[36:37], v[2:3] op_sel_hi:[1,0]
	v_pk_mul_f32 v[34:35], v[34:35], v[2:3] op_sel_hi:[1,0]
	v_pk_mul_f32 v[32:33], v[32:33], v[2:3] op_sel_hi:[1,0]
	v_pk_mul_f32 v[30:31], v[30:31], v[2:3] op_sel_hi:[1,0]
	v_pk_mul_f32 v[28:29], v[28:29], v[2:3] op_sel_hi:[1,0]
	v_pk_mul_f32 v[26:27], v[26:27], v[2:3] op_sel_hi:[1,0]
	v_pk_mul_f32 v[24:25], v[24:25], v[2:3] op_sel_hi:[1,0]
	v_pk_mul_f32 v[22:23], v[22:23], v[2:3] op_sel_hi:[1,0]
	v_pk_mul_f32 v[20:21], v[20:21], v[2:3] op_sel_hi:[1,0]
	v_pk_mul_f32 v[18:19], v[18:19], v[2:3] op_sel_hi:[1,0]
	v_mul_f32_e32 v250, v250, v2

; template <int DQK, bool CAUSAL, bool ROPE> ...
;     ...
;     if (grp == 1) AT_PV(ntiles - 1, vprev);
.LBB0_899:
	s_and_b64 vcc, exec, s[88:89]
	s_cbranch_vccz .LBB0_881
	s_lshl_b32 s0, s33, 6
	s_sub_i32 s0, s0, 64
	s_cmp_gt_i32 s0, s64
	s_cbranch_scc1 .LBB0_881
	s_mul_i32 s0, s71, 0x4800
	v_add_u32_e32 v17, s0, v244
	ds_read_b128 v[4:7], v17 offset:51200
	ds_read_b128 v[8:11], v17 offset:55808
	ds_read_b128 v[12:15], v17 offset:60416
	ds_read_b128 v[176:179], v17 offset:65024
	s_nop 8
	v_max3_f32 v2, v98, v99, v100
	v_max3_f32 v16, v101, v102, v103
	v_max3_f32 v174, v104, v105, v106
	v_max3_f32 v175, v107, v108, v109
	v_max3_f32 v2, v2, v110, v111
	v_max3_f32 v16, v16, v112, v113
	v_max3_f32 v174, v174, v82, v83
	v_max3_f32 v175, v175, v84, v85
	v_max3_f32 v2, v2, v86, v87
	v_max3_f32 v16, v16, v88, v89
	v_max3_f32 v174, v174, v90, v91
	v_max3_f32 v175, v175, v92, v93
	v_max3_f32 v2, v2, v94, v95
	v_max3_f32 v16, v16, v96, v97
	v_max3_f32 v2, v2, v16, v174
	v_max_f32_e32 v2, v2, v175
	v_mov_b32_e32 v16, v2
	s_nop 1
	v_permlane32_swap_b32_e32 v2, v16
	v_max_f32_e32 v2, v2, v16
	v_sub_f32_e32 v16, v2, v252
	v_mul_f32_e32 v16, 0x3dd53b94, v16
	s_mov_b32 s0, 0x41380000
	v_cmp_ge_f32_e32 vcc, s0, v16
	s_cmp_eq_u64 vcc, exec
	s_cbranch_scc1 .Ld3_exp
	v_max_f32_e32 v2, v2, v2
	v_max_f32_e32 v16, v252, v252
	v_max_f32_e32 v16, v16, v2
	v_sub_f32_e32 v2, v252, v16
	v_mul_f32_e32 v2, 0x3dd53b94, v2
	v_exp_f32_e32 v2, v2
	v_mov_b32_e32 v252, v16
	v_pk_mul_f32 v[80:81], v[80:81], v[2:3] op_sel_hi:[1,0]
	v_pk_mul_f32 v[78:79], v[78:79], v[2:3] op_sel_hi:[1,0]
	v_pk_mul_f32 v[76:77], v[76:77], v[2:3] op_sel_hi:[1,0]
	v_pk_mul_f32 v[74:75], v[74:75], v[2:3] op_sel_hi:[1,0]
	v_pk_mul_f32 v[72:73], v[72:73], v[2:3] op_sel_hi:[1,0]
	v_pk_mul_f32 v[70:71], v[70:71], v[2:3] op_sel_hi:[1,0]
	v_pk_mul_f32 v[68:69], v[68:69], v[2:3] op_sel_hi:[1,0]
	v_pk_mul_f32 v[66:67], v[66:67], v[2:3] op_sel_hi:[1,0]
	v_pk_mul_f32 v[64:65], v[64:65], v[2:3] op_sel_hi:[1,0]
	v_pk_mul_f32 v[62:63], v[62:63], v[2:3] op_sel_hi:[1,0]
	v_pk_mul_f32 v[60:61], v[60:61], v[2:3] op_sel_hi:[1,0]
	v_pk_mul_f32 v[58:59], v[58:59], v[2:3] op_sel_hi:[1,0]
	v_pk_mul_f32 v[56:57], v[56:57], v[2:3] op_sel_hi:[1,0]
	v_pk_mul_f32 v[54:55], v[54:55], v[2:3] op_sel_hi:[1,0]
	v_pk_mul_f32 v[52:53], v[52:53], v[2:3] op_sel_hi:[1,0]
	v_pk_mul_f32 v[50:51], v[50:51], v[2:3] op_sel_hi:[1,0]
	v_pk_mul_f32 v[48:49], v[48:49], v[2:3] op_sel_hi:[1,0]
	v_pk_mul_f32 v[46:47], v[46:47], v[2:3] op_sel_hi:[1,0]
	v_pk_mul_f32 v[44:45], v[44:45], v[2:3] op_sel_hi:[1,0]
	v_pk_mul_f32 v[42:43], v[42:43], v[2:3] op_sel_hi:[1,0]
	v_pk_mul_f32 v[40:41], v[40:41], v[2:3] op_sel_hi:[1,0]
	v_pk_mul_f32 v[38:39], v[38:39], v[2:3] op_sel_hi:[1,0]
	v_pk_mul_f32 v[36:37], v[36:37], v[2:3] op_sel_hi:[1,0]
	v_pk_mul_f32 v[34:35], v[34:35], v[2:3] op_sel_hi:[1,0]
	v_pk_mul_f32 v[32:33], v[32:33], v[2:3] op_sel_hi:[1,0]
	v_pk_mul_f32 v[30:31], v[30:31], v[2:3] op_sel_hi:[1,0]
	v_pk_mul_f32 v[28:29], v[28:29], v[2:3] op_sel_hi:[1,0]
	v_pk_mul_f32 v[26:27], v[26:27], v[2:3] op_sel_hi:[1,0]
	v_pk_mul_f32 v[24:25], v[24:25], v[2:3] op_sel_hi:[1,0]
	v_pk_mul_f32 v[22:23], v[22:23], v[2:3] op_sel_hi:[1,0]
	v_pk_mul_f32 v[20:21], v[20:21], v[2:3] op_sel_hi:[1,0]
	v_pk_mul_f32 v[18:19], v[18:19], v[2:3] op_sel_hi:[1,0]
	v_mul_f32_e32 v250, v250, v2
